# phase1 rmsnorm: hand-written row loop, both rows of an iteration requested up front (16 loads in flight), packed fma sums of squares, interleaved cross-lane reductions
# baseline (speedup 1.0000x reference)
.LBB0_79:
	v_lshl_add_u64 v[150:151], v[116:117], 0, s[8:9]
	global_load_dwordx4 v[80:83], v[114:115], off offset:-4096
	global_load_dwordx4 v[84:87], v[114:115], off offset:-3072
	global_load_dwordx4 v[142:145], v[114:115], off offset:-2048
	global_load_dwordx4 v[88:91], v[114:115], off offset:-1024
	global_load_dwordx4 v[72:75], v[114:115], off
	global_load_dwordx4 v[68:71], v[114:115], off offset:1024
	global_load_dwordx4 v[76:79], v[114:115], off offset:2048
	global_load_dwordx4 v[64:67], v[114:115], off offset:3072
	v_add_co_u32_e32 v242, vcc, 0x2000, v114
	s_add_u32 s8, s8, 0x2000
	s_addc_u32 s9, s9, 0
	v_addc_co_u32_e32 v243, vcc, 0, v115, vcc
	global_load_dwordx4 v[204:207], v[242:243], off offset:-4096
	global_load_dwordx4 v[208:211], v[242:243], off offset:-3072
	global_load_dwordx4 v[212:215], v[242:243], off offset:-2048
	global_load_dwordx4 v[216:219], v[242:243], off offset:-1024
	global_load_dwordx4 v[220:223], v[242:243], off
	global_load_dwordx4 v[224:227], v[242:243], off offset:1024
	global_load_dwordx4 v[228:231], v[242:243], off offset:2048
	global_load_dwordx4 v[232:235], v[242:243], off offset:3072
	v_add_co_u32_e32 v244, vcc, 0x1000, v150
	s_mov_b64 s[10:11], 0x4000
	s_nop 0
	v_addc_co_u32_e32 v245, vcc, 0, v151, vcc
	v_lshl_add_u64 v[114:115], v[114:115], 0, s[10:11]
	s_waitcnt vmcnt(15)
	v_pk_mul_f32 v[236:237], v[80:81], v[80:81]
	v_pk_mul_f32 v[238:239], v[82:83], v[82:83]
	s_waitcnt vmcnt(14)
	v_pk_fma_f32 v[236:237], v[84:85], v[84:85], v[236:237]
	v_pk_fma_f32 v[238:239], v[86:87], v[86:87], v[238:239]
	s_waitcnt vmcnt(13)
	v_pk_fma_f32 v[236:237], v[142:143], v[142:143], v[236:237]
	v_pk_fma_f32 v[238:239], v[144:145], v[144:145], v[238:239]
	s_waitcnt vmcnt(12)
	v_pk_fma_f32 v[236:237], v[88:89], v[88:89], v[236:237]
	v_pk_fma_f32 v[238:239], v[90:91], v[90:91], v[238:239]
	s_waitcnt vmcnt(11)
	v_pk_fma_f32 v[236:237], v[72:73], v[72:73], v[236:237]
	v_pk_fma_f32 v[238:239], v[74:75], v[74:75], v[238:239]
	s_waitcnt vmcnt(10)
	v_pk_fma_f32 v[236:237], v[68:69], v[68:69], v[236:237]
	v_pk_fma_f32 v[238:239], v[70:71], v[70:71], v[238:239]
	s_waitcnt vmcnt(9)
	v_pk_fma_f32 v[236:237], v[76:77], v[76:77], v[236:237]
	v_pk_fma_f32 v[238:239], v[78:79], v[78:79], v[238:239]
	s_waitcnt vmcnt(8)
	v_pk_fma_f32 v[236:237], v[64:65], v[64:65], v[236:237]
	v_pk_fma_f32 v[238:239], v[66:67], v[66:67], v[238:239]
	s_waitcnt vmcnt(7)
	v_pk_mul_f32 v[240:241], v[204:205], v[204:205]
	v_pk_mul_f32 v[246:247], v[206:207], v[206:207]
	s_waitcnt vmcnt(6)
	v_pk_fma_f32 v[240:241], v[208:209], v[208:209], v[240:241]
	v_pk_fma_f32 v[246:247], v[210:211], v[210:211], v[246:247]
	s_waitcnt vmcnt(5)
	v_pk_fma_f32 v[240:241], v[212:213], v[212:213], v[240:241]
	v_pk_fma_f32 v[246:247], v[214:215], v[214:215], v[246:247]
	s_waitcnt vmcnt(4)
	v_pk_fma_f32 v[240:241], v[216:217], v[216:217], v[240:241]
	v_pk_fma_f32 v[246:247], v[218:219], v[218:219], v[246:247]
	s_waitcnt vmcnt(3)
	v_pk_fma_f32 v[240:241], v[220:221], v[220:221], v[240:241]
	v_pk_fma_f32 v[246:247], v[222:223], v[222:223], v[246:247]
	s_waitcnt vmcnt(2)
	v_pk_fma_f32 v[240:241], v[224:225], v[224:225], v[240:241]
	v_pk_fma_f32 v[246:247], v[226:227], v[226:227], v[246:247]
	s_waitcnt vmcnt(1)
	v_pk_fma_f32 v[240:241], v[228:229], v[228:229], v[240:241]
	v_pk_fma_f32 v[246:247], v[230:231], v[230:231], v[246:247]
	s_waitcnt vmcnt(0)
	v_pk_fma_f32 v[240:241], v[232:233], v[232:233], v[240:241]
	v_pk_fma_f32 v[246:247], v[234:235], v[234:235], v[246:247]
	v_pk_add_f32 v[236:237], v[236:237], v[238:239]
	v_pk_add_f32 v[240:241], v[240:241], v[246:247]
	s_nop 0
	v_add_f32_e32 v236, v236, v237
	v_add_f32_e32 v240, v240, v241
	ds_bpermute_b32 v238, v121, v236
	ds_bpermute_b32 v239, v121, v240
	s_waitcnt lgkmcnt(0)
	v_add_f32_e32 v236, v236, v238
	v_add_f32_e32 v240, v240, v239
	ds_bpermute_b32 v238, v122, v236
	ds_bpermute_b32 v239, v122, v240
	s_waitcnt lgkmcnt(0)
	v_add_f32_e32 v236, v236, v238
	v_add_f32_e32 v240, v240, v239
	ds_bpermute_b32 v238, v123, v236
	ds_bpermute_b32 v239, v123, v240
	s_waitcnt lgkmcnt(0)
	v_add_f32_e32 v236, v236, v238
	v_add_f32_e32 v240, v240, v239
	ds_bpermute_b32 v238, v124, v236
	ds_bpermute_b32 v239, v124, v240
	s_waitcnt lgkmcnt(0)
	v_add_f32_e32 v236, v236, v238
	v_add_f32_e32 v240, v240, v239
	ds_bpermute_b32 v238, v125, v236
	ds_bpermute_b32 v239, v125, v240
	s_waitcnt lgkmcnt(0)
	v_add_f32_e32 v236, v236, v238
	v_add_f32_e32 v240, v240, v239
	ds_bpermute_b32 v238, v126, v236
	ds_bpermute_b32 v239, v126, v240
	s_waitcnt lgkmcnt(0)
	v_add_f32_e32 v236, v236, v238
	v_add_f32_e32 v240, v240, v239
	v_fmamk_f32 v236, v236, 0x3a000000, v141
	v_fmamk_f32 v240, v240, 0x3a000000, v141
	v_mul_f32_e32 v238, 0x4b800000, v236
	v_cmp_gt_f32_e32 vcc, s33, v236
	v_mul_f32_e32 v239, 0x4b800000, v240
	v_cmp_gt_f32_e64 s[10:11], s33, v240
	s_nop 0
	v_cndmask_b32_e32 v236, v236, v238, vcc
	v_cndmask_b32_e64 v240, v240, v239, s[10:11]
	v_rsq_f32_e32 v236, v236
	v_rsq_f32_e32 v240, v240
	s_nop 0
	v_mul_f32_e32 v238, 0x45800000, v236
	v_mul_f32_e32 v239, 0x45800000, v240
	v_cndmask_b32_e32 v152, v236, v238, vcc
	v_cndmask_b32_e64 v154, v240, v239, s[10:11]
	v_pk_mul_f32 v[80:81], v[80:81], v[152:153] op_sel_hi:[1,0]
	v_pk_mul_f32 v[82:83], v[82:83], v[152:153] op_sel_hi:[1,0]
	v_pk_mul_f32 v[80:81], v[172:173], v[80:81]
	v_pk_mul_f32 v[82:83], v[174:175], v[82:83]
	v_pk_fma_f32 v[80:81], v[8:9], v[80:81], v[0:1]
	v_pk_fma_f32 v[82:83], v[10:11], v[82:83], v[2:3]
	v_cvt_pk_bf16_f32 v80, v80, v81
	v_cvt_pk_bf16_f32 v81, v82, v83
	global_store_dwordx2 v[150:151], v[80:81], off
	v_pk_mul_f32 v[84:85], v[84:85], v[152:153] op_sel_hi:[1,0]
	v_pk_mul_f32 v[86:87], v[86:87], v[152:153] op_sel_hi:[1,0]
	v_pk_mul_f32 v[84:85], v[176:177], v[84:85]
	v_pk_mul_f32 v[86:87], v[178:179], v[86:87]
	v_pk_fma_f32 v[84:85], v[12:13], v[84:85], v[4:5]
	v_pk_fma_f32 v[86:87], v[14:15], v[86:87], v[6:7]
	v_cvt_pk_bf16_f32 v84, v84, v85
	v_cvt_pk_bf16_f32 v85, v86, v87
	global_store_dwordx2 v[150:151], v[84:85], off offset:512
	v_pk_mul_f32 v[142:143], v[142:143], v[152:153] op_sel_hi:[1,0]
	v_pk_mul_f32 v[144:145], v[144:145], v[152:153] op_sel_hi:[1,0]
	v_pk_mul_f32 v[142:143], v[180:181], v[142:143]
	v_pk_mul_f32 v[144:145], v[182:183], v[144:145]
	v_pk_fma_f32 v[142:143], v[24:25], v[142:143], v[16:17]
	v_pk_fma_f32 v[144:145], v[26:27], v[144:145], v[18:19]
	v_cvt_pk_bf16_f32 v142, v142, v143
	v_cvt_pk_bf16_f32 v143, v144, v145
	global_store_dwordx2 v[150:151], v[142:143], off offset:1024
	v_pk_mul_f32 v[88:89], v[88:89], v[152:153] op_sel_hi:[1,0]
	v_pk_mul_f32 v[90:91], v[90:91], v[152:153] op_sel_hi:[1,0]
	v_pk_mul_f32 v[88:89], v[184:185], v[88:89]
	v_pk_mul_f32 v[90:91], v[186:187], v[90:91]
	v_pk_fma_f32 v[88:89], v[28:29], v[88:89], v[20:21]
	v_pk_fma_f32 v[90:91], v[30:31], v[90:91], v[22:23]
	v_cvt_pk_bf16_f32 v88, v88, v89
	v_cvt_pk_bf16_f32 v89, v90, v91
	global_store_dwordx2 v[150:151], v[88:89], off offset:1536
	v_pk_mul_f32 v[72:73], v[72:73], v[152:153] op_sel_hi:[1,0]
	v_pk_mul_f32 v[74:75], v[74:75], v[152:153] op_sel_hi:[1,0]
	v_pk_mul_f32 v[72:73], v[188:189], v[72:73]
	v_pk_mul_f32 v[74:75], v[190:191], v[74:75]
	v_pk_fma_f32 v[72:73], v[40:41], v[72:73], v[32:33]
	v_pk_fma_f32 v[74:75], v[42:43], v[74:75], v[34:35]
	v_cvt_pk_bf16_f32 v72, v72, v73
	v_cvt_pk_bf16_f32 v73, v74, v75
	global_store_dwordx2 v[150:151], v[72:73], off offset:2048
	v_pk_mul_f32 v[68:69], v[68:69], v[152:153] op_sel_hi:[1,0]
	v_pk_mul_f32 v[70:71], v[70:71], v[152:153] op_sel_hi:[1,0]
	v_pk_mul_f32 v[68:69], v[192:193], v[68:69]
	v_pk_mul_f32 v[70:71], v[194:195], v[70:71]
	v_pk_fma_f32 v[68:69], v[44:45], v[68:69], v[36:37]
	v_pk_fma_f32 v[70:71], v[46:47], v[70:71], v[38:39]
	v_cvt_pk_bf16_f32 v68, v68, v69
	v_cvt_pk_bf16_f32 v69, v70, v71
	global_store_dwordx2 v[150:151], v[68:69], off offset:2560
	v_pk_mul_f32 v[76:77], v[76:77], v[152:153] op_sel_hi:[1,0]
	v_pk_mul_f32 v[78:79], v[78:79], v[152:153] op_sel_hi:[1,0]
	v_pk_mul_f32 v[76:77], v[196:197], v[76:77]
	v_pk_mul_f32 v[78:79], v[198:199], v[78:79]
	v_pk_fma_f32 v[76:77], v[56:57], v[76:77], v[48:49]
	v_pk_fma_f32 v[78:79], v[58:59], v[78:79], v[50:51]
	v_cvt_pk_bf16_f32 v76, v76, v77
	v_cvt_pk_bf16_f32 v77, v78, v79
	global_store_dwordx2 v[150:151], v[76:77], off offset:3072
	v_pk_mul_f32 v[64:65], v[64:65], v[152:153] op_sel_hi:[1,0]
	v_pk_mul_f32 v[66:67], v[66:67], v[152:153] op_sel_hi:[1,0]
	v_pk_mul_f32 v[64:65], v[200:201], v[64:65]
	v_pk_mul_f32 v[66:67], v[202:203], v[66:67]
	v_pk_fma_f32 v[64:65], v[60:61], v[64:65], v[52:53]
	v_pk_fma_f32 v[66:67], v[62:63], v[66:67], v[54:55]
	v_cvt_pk_bf16_f32 v64, v64, v65
	v_cvt_pk_bf16_f32 v65, v66, v67
	global_store_dwordx2 v[150:151], v[64:65], off offset:3584
	v_pk_mul_f32 v[204:205], v[204:205], v[154:155] op_sel_hi:[1,0]
	v_pk_mul_f32 v[206:207], v[206:207], v[154:155] op_sel_hi:[1,0]
	v_pk_mul_f32 v[204:205], v[172:173], v[204:205]
	v_pk_mul_f32 v[206:207], v[174:175], v[206:207]
	v_pk_fma_f32 v[204:205], v[8:9], v[204:205], v[0:1]
	v_pk_fma_f32 v[206:207], v[10:11], v[206:207], v[2:3]
	v_cvt_pk_bf16_f32 v204, v204, v205
	v_cvt_pk_bf16_f32 v205, v206, v207
	global_store_dwordx2 v[244:245], v[204:205], off
	v_pk_mul_f32 v[208:209], v[208:209], v[154:155] op_sel_hi:[1,0]
	v_pk_mul_f32 v[210:211], v[210:211], v[154:155] op_sel_hi:[1,0]
	v_pk_mul_f32 v[208:209], v[176:177], v[208:209]
	v_pk_mul_f32 v[210:211], v[178:179], v[210:211]
	v_pk_fma_f32 v[208:209], v[12:13], v[208:209], v[4:5]
	v_pk_fma_f32 v[210:211], v[14:15], v[210:211], v[6:7]
	v_cvt_pk_bf16_f32 v208, v208, v209
	v_cvt_pk_bf16_f32 v209, v210, v211
	global_store_dwordx2 v[244:245], v[208:209], off offset:512
	v_pk_mul_f32 v[212:213], v[212:213], v[154:155] op_sel_hi:[1,0]
	v_pk_mul_f32 v[214:215], v[214:215], v[154:155] op_sel_hi:[1,0]
	v_pk_mul_f32 v[212:213], v[180:181], v[212:213]
	v_pk_mul_f32 v[214:215], v[182:183], v[214:215]
	v_pk_fma_f32 v[212:213], v[24:25], v[212:213], v[16:17]
	v_pk_fma_f32 v[214:215], v[26:27], v[214:215], v[18:19]
	v_cvt_pk_bf16_f32 v212, v212, v213
	v_cvt_pk_bf16_f32 v213, v214, v215
	global_store_dwordx2 v[244:245], v[212:213], off offset:1024
	v_pk_mul_f32 v[216:217], v[216:217], v[154:155] op_sel_hi:[1,0]
	v_pk_mul_f32 v[218:219], v[218:219], v[154:155] op_sel_hi:[1,0]
	v_pk_mul_f32 v[216:217], v[184:185], v[216:217]
	v_pk_mul_f32 v[218:219], v[186:187], v[218:219]
	v_pk_fma_f32 v[216:217], v[28:29], v[216:217], v[20:21]
	v_pk_fma_f32 v[218:219], v[30:31], v[218:219], v[22:23]
	v_cvt_pk_bf16_f32 v216, v216, v217
	v_cvt_pk_bf16_f32 v217, v218, v219
	global_store_dwordx2 v[244:245], v[216:217], off offset:1536
	v_pk_mul_f32 v[220:221], v[220:221], v[154:155] op_sel_hi:[1,0]
	v_pk_mul_f32 v[222:223], v[222:223], v[154:155] op_sel_hi:[1,0]
	v_pk_mul_f32 v[220:221], v[188:189], v[220:221]
	v_pk_mul_f32 v[222:223], v[190:191], v[222:223]
	v_pk_fma_f32 v[220:221], v[40:41], v[220:221], v[32:33]
	v_pk_fma_f32 v[222:223], v[42:43], v[222:223], v[34:35]
	v_cvt_pk_bf16_f32 v220, v220, v221
	v_cvt_pk_bf16_f32 v221, v222, v223
	global_store_dwordx2 v[244:245], v[220:221], off offset:2048
	v_pk_mul_f32 v[224:225], v[224:225], v[154:155] op_sel_hi:[1,0]
	v_pk_mul_f32 v[226:227], v[226:227], v[154:155] op_sel_hi:[1,0]
	v_pk_mul_f32 v[224:225], v[192:193], v[224:225]
	v_pk_mul_f32 v[226:227], v[194:195], v[226:227]
	v_pk_fma_f32 v[224:225], v[44:45], v[224:225], v[36:37]
	v_pk_fma_f32 v[226:227], v[46:47], v[226:227], v[38:39]
	v_cvt_pk_bf16_f32 v224, v224, v225
	v_cvt_pk_bf16_f32 v225, v226, v227
	global_store_dwordx2 v[244:245], v[224:225], off offset:2560
	v_pk_mul_f32 v[228:229], v[228:229], v[154:155] op_sel_hi:[1,0]
	v_pk_mul_f32 v[230:231], v[230:231], v[154:155] op_sel_hi:[1,0]
	v_pk_mul_f32 v[228:229], v[196:197], v[228:229]
	v_pk_mul_f32 v[230:231], v[198:199], v[230:231]
	v_pk_fma_f32 v[228:229], v[56:57], v[228:229], v[48:49]
	v_pk_fma_f32 v[230:231], v[58:59], v[230:231], v[50:51]
	v_cvt_pk_bf16_f32 v228, v228, v229
	v_cvt_pk_bf16_f32 v229, v230, v231
	global_store_dwordx2 v[244:245], v[228:229], off offset:3072
	v_pk_mul_f32 v[232:233], v[232:233], v[154:155] op_sel_hi:[1,0]
	v_pk_mul_f32 v[234:235], v[234:235], v[154:155] op_sel_hi:[1,0]
	v_pk_mul_f32 v[232:233], v[200:201], v[232:233]
	v_pk_mul_f32 v[234:235], v[202:203], v[234:235]
	v_pk_fma_f32 v[232:233], v[60:61], v[232:233], v[52:53]
	v_pk_fma_f32 v[234:235], v[62:63], v[234:235], v[54:55]
	v_cvt_pk_bf16_f32 v232, v232, v233
	v_cvt_pk_bf16_f32 v233, v234, v235
	global_store_dwordx2 v[244:245], v[232:233], off offset:3584
	s_cmp_eq_u32 s8, 0x8000
	s_cbranch_scc0 .LBB0_79
	s_add_i32 s38, s38, s72
	v_add_u32_e32 v140, s2, v140
	s_cmpk_gt_i32 s38, 0xff
	v_add_u32_e32 v108, s2, v108
	s_cbranch_scc0 .LBB0_66
